# code placement: G2 phase shifted by 16 bytes (s_nop padding before, compensating padding after so later phases keep their placement)
# speedup vs baseline: 1.0035x; 1.0035x over previous
.Lxb2_done:
	s_nop 0
	s_nop 0
	s_nop 0
	s_nop 0
	s_waitcnt vmcnt(1)

.Lxb3_top:
	s_nop 0
	s_nop 0
	s_nop 0
	s_nop 0
	s_nop 0
	s_nop 0
	s_nop 0
	s_nop 0
	s_nop 0
	s_nop 0
	s_nop 0
	s_nop 0
	s_waitcnt vmcnt(0) lgkmcnt(0)
	v_mov_b32_e32 v1, 1
	v_readlane_b32 s11, v244, 43
	s_cmp_eq_u32 s11, 1
	s_cbranch_scc0 .Lxb3_glob
	s_and_b32 s12, s2, 7
	s_lshl_b32 s10, s12, 8
	s_add_i32 s10, s10, 0x6000
	v_mov_b32_e32 v6, s10
	global_atomic_add v6, v1, s[92:93]
	buffer_inv sc1
	v_readlane_b32 s11, v244, 41
	s_sub_i32 s11, s11, s12
	s_add_i32 s11, s11, 7
	s_lshr_b32 s11, s11, 3
	s_mul_i32 s6, s11, 3
	s_branch .Lxb3_wait
